# attention: max-subtraction folded into QK accumulator init (SrcC=-m), DMA source advanced by SGPR base: 40 fewer VALU per tile
# speedup vs baseline: 1.0824x; 1.0165x over previous
.Lat_entry:
	s_mov_b32 s92, m0
	s_add_i32 s71, s97, 0x10000
	s_mov_b32 s70, 0
	s_movk_i32 s81, 0x7f
	s_mov_b32 s80, 0x20000
	s_add_i32 s51, s90, 0x80000
	s_add_u32 s50, s62, s51
	s_addc_u32 s51, s63, 0
	s_mov_b32 s94, 0xff800000
	v_mov_b32_e32 v246, 0
	v_mov_b32_e32 v247, 0
	v_mov_b32_e32 v248, 0
	v_mov_b32_e32 v249, 0
	v_mov_b32_e32 v250, 0
	v_mov_b32_e32 v251, 0
	v_mov_b32_e32 v252, 0
	v_mov_b32_e32 v253, 0
	v_readlane_b32 s4, v254, 24
	v_and_b32_e32 v234, 15, v211
	v_lshrrev_b32_e32 v235, 4, v211
	v_xor_b32_e32 v236, v234, v235
	v_lshlrev_b32_e32 v236, 4, v236
	v_lshl_add_u32 v236, v234, 8, v236
	v_add_u32_e32 v221, s4, v236
	v_lshlrev_b32_e32 v237, 2, v235
	v_sub_u32_e32 v237, v234, v237
	v_add_u32_e32 v223, s3, v237
	v_bfe_u32 v237, v211, 5, 1
	v_lshlrev_b32_e32 v237, 12, v237
	v_bfe_u32 v238, v211, 4, 1
	v_lshl_add_u32 v237, v238, 7, v237
	v_bfe_u32 v238, v211, 2, 2
	v_lshl_add_u32 v237, v238, 5, v237
	v_and_b32_e32 v238, 3, v211
	v_lshl_add_u32 v237, v238, 3, v237
	v_add_u32_e32 v222, 0x8000, v237
	v_mov_b32_e32 v243, v233
	v_mov_b32_e32 v244, 0
	v_xor_b32_e32 v234, s70, v221
	v_xor_b32_e32 v235, 64, v234
	v_xor_b32_e32 v236, 0x80, v234
	v_xor_b32_e32 v237, 0xc0, v234
.Lat_loop:
	s_waitcnt vmcnt(0) lgkmcnt(0)
	s_barrier
	s_cmp_gt_u32 s58, s89
	s_cbranch_scc1 .Lat_inactive
	ds_read_b128 v[162:165], v234
	ds_read_b128 v[166:169], v235
	ds_read_b128 v[170:173], v236
	ds_read_b128 v[174:177], v237
	v_add_u32_e32 v242, s70, v222
	s_add_i32 m0, s71, 0x0
	s_nop 0
	global_load_lds_dwordx4 v231, s[50:51]
	s_add_i32 m0, s71, 0x400
	s_nop 0
	global_load_lds_dwordx4 v229, s[50:51]
	s_waitcnt lgkmcnt(3)
	v_mfma_f32_16x16x32_bf16 v[130:133], v[162:165], v[178:181], v[246:249]
	v_mfma_f32_16x16x32_bf16 v[146:149], v[162:165], v[194:197], v[250:253]
	ds_read_b128 v[162:165], v234 offset:4096
	s_waitcnt lgkmcnt(3)
	v_mfma_f32_16x16x32_bf16 v[130:133], v[166:169], v[182:185], v[130:133]
	v_mfma_f32_16x16x32_bf16 v[146:149], v[166:169], v[198:201], v[146:149]
	ds_read_b128 v[166:169], v235 offset:4096
	s_add_i32 m0, s71, 0x800
	s_nop 0
	global_load_lds_dwordx4 v227, s[50:51]
	s_waitcnt lgkmcnt(3)
	v_mfma_f32_16x16x32_bf16 v[130:133], v[170:173], v[186:189], v[130:133]
	v_mfma_f32_16x16x32_bf16 v[146:149], v[170:173], v[202:205], v[146:149]
	ds_read_b128 v[170:173], v236 offset:4096
	s_waitcnt lgkmcnt(3)
	v_mfma_f32_16x16x32_bf16 v[130:133], v[174:177], v[190:193], v[130:133]
	v_mfma_f32_16x16x32_bf16 v[146:149], v[174:177], v[206:209], v[146:149]
	ds_read_b128 v[174:177], v237 offset:4096
	s_add_i32 m0, s71, 0xc00
	s_nop 0
	global_load_lds_dwordx4 v225, s[50:51]
	s_waitcnt lgkmcnt(3)
	v_mfma_f32_16x16x32_bf16 v[134:137], v[162:165], v[178:181], v[246:249]
	v_mfma_f32_16x16x32_bf16 v[150:153], v[162:165], v[194:197], v[250:253]
	ds_read_b128 v[162:165], v234 offset:8192
	s_waitcnt lgkmcnt(3)
	v_mfma_f32_16x16x32_bf16 v[134:137], v[166:169], v[182:185], v[134:137]
	v_mfma_f32_16x16x32_bf16 v[150:153], v[166:169], v[198:201], v[150:153]
	ds_read_b128 v[166:169], v235 offset:8192
	s_add_i32 m0, s71, 0x1000
	s_nop 0
	global_load_lds_dwordx4 v230, s[50:51]
	s_waitcnt lgkmcnt(3)
	v_mfma_f32_16x16x32_bf16 v[134:137], v[170:173], v[186:189], v[134:137]
	v_mfma_f32_16x16x32_bf16 v[150:153], v[170:173], v[202:205], v[150:153]
	ds_read_b128 v[170:173], v236 offset:8192
	s_waitcnt lgkmcnt(3)
	v_mfma_f32_16x16x32_bf16 v[134:137], v[174:177], v[190:193], v[134:137]
	v_mfma_f32_16x16x32_bf16 v[150:153], v[174:177], v[206:209], v[150:153]
	ds_read_b128 v[174:177], v237 offset:8192
	s_add_i32 m0, s71, 0x1400
	s_nop 0
	global_load_lds_dwordx4 v228, s[50:51]
	s_waitcnt lgkmcnt(3)
	v_mfma_f32_16x16x32_bf16 v[138:141], v[162:165], v[178:181], v[246:249]
	v_mfma_f32_16x16x32_bf16 v[154:157], v[162:165], v[194:197], v[250:253]
	ds_read_b128 v[162:165], v234 offset:12288
	s_waitcnt lgkmcnt(3)
	v_mfma_f32_16x16x32_bf16 v[138:141], v[166:169], v[182:185], v[138:141]
	v_mfma_f32_16x16x32_bf16 v[154:157], v[166:169], v[198:201], v[154:157]
	ds_read_b128 v[166:169], v235 offset:12288
	s_add_i32 m0, s71, 0x1800
	s_nop 0
	global_load_lds_dwordx4 v226, s[50:51]
	s_waitcnt lgkmcnt(3)
	v_mfma_f32_16x16x32_bf16 v[138:141], v[170:173], v[186:189], v[138:141]
	v_mfma_f32_16x16x32_bf16 v[154:157], v[170:173], v[202:205], v[154:157]
	ds_read_b128 v[170:173], v236 offset:12288
	s_waitcnt lgkmcnt(3)
	v_mfma_f32_16x16x32_bf16 v[138:141], v[174:177], v[190:193], v[138:141]
	v_mfma_f32_16x16x32_bf16 v[154:157], v[174:177], v[206:209], v[154:157]
	ds_read_b128 v[174:177], v237 offset:12288
	s_add_i32 m0, s71, 0x1c00
	s_nop 0
	global_load_lds_dwordx4 v224, s[50:51]
	s_waitcnt lgkmcnt(3)
	v_mfma_f32_16x16x32_bf16 v[142:145], v[162:165], v[178:181], v[246:249]
	v_mfma_f32_16x16x32_bf16 v[158:161], v[162:165], v[194:197], v[250:253]
	ds_read_b64_tr_b16 v[162:163], v242 offset:0
	ds_read_b64_tr_b16 v[164:165], v242 offset:8192
	s_waitcnt lgkmcnt(4)
	v_mfma_f32_16x16x32_bf16 v[142:145], v[166:169], v[182:185], v[142:145]
	v_mfma_f32_16x16x32_bf16 v[158:161], v[166:169], v[198:201], v[158:161]
	ds_read_b64_tr_b16 v[166:167], v242 offset:16384
	ds_read_b64_tr_b16 v[168:169], v242 offset:24576
	s_waitcnt lgkmcnt(5)
	v_mfma_f32_16x16x32_bf16 v[142:145], v[170:173], v[186:189], v[142:145]
	v_mfma_f32_16x16x32_bf16 v[158:161], v[170:173], v[202:205], v[158:161]
	ds_read_b64_tr_b16 v[170:171], v242 offset:256
	ds_read_b64_tr_b16 v[172:173], v242 offset:8448
	s_waitcnt lgkmcnt(6)
	v_mfma_f32_16x16x32_bf16 v[142:145], v[174:177], v[190:193], v[142:145]
	v_mfma_f32_16x16x32_bf16 v[158:161], v[174:177], v[206:209], v[158:161]
	ds_read_b64_tr_b16 v[174:175], v242 offset:16640
	ds_read_b64_tr_b16 v[176:177], v242 offset:24832
	s_add_i32 s4, s91, 0xb0
	s_cmp_le_u32 s4, s3
	s_cbranch_scc0 .Lat_diag_a
.Lat_sm_a:
	v_max3_f32 v238, v130, v131, v132
	v_max3_f32 v239, v146, v147, v148
	v_max3_f32 v238, v238, v133, v134
	v_max3_f32 v239, v239, v149, v150
	v_max3_f32 v238, v238, v135, v136
	v_max3_f32 v239, v239, v151, v152
	v_max3_f32 v238, v238, v137, v138
	v_max3_f32 v239, v239, v153, v154
	v_max3_f32 v238, v238, v139, v140
	v_max3_f32 v239, v239, v155, v156
	v_max3_f32 v238, v238, v141, v142
	v_max3_f32 v239, v239, v157, v158
	v_max3_f32 v238, v238, v143, v144
	v_max3_f32 v239, v239, v159, v160
	v_max_f32_e32 v238, v238, v145
	v_max_f32_e32 v239, v239, v161
	s_cmp_eq_u32 s58, 0
	s_cbranch_scc1 .Lat_resc_a
	v_max_f32_e32 v240, v238, v239
	v_cmp_ge_f32_e32 vcc, s74, v240
	s_cmp_eq_u64 vcc, exec
	s_cbranch_scc0 .Lat_resc_a
.Lat_exp_a:
	v_exp_f32_e32 v130, v130
	v_exp_f32_e32 v131, v131
	v_exp_f32_e32 v132, v132
	v_add_f32_e32 v0, v130, v131
	v_exp_f32_e32 v133, v133
	v_add_f32_e32 v0, v0, v132
	v_exp_f32_e32 v134, v134
	v_add_f32_e32 v0, v0, v133
	v_exp_f32_e32 v135, v135
	v_add_f32_e32 v0, v0, v134
	v_exp_f32_e32 v136, v136
	v_add_f32_e32 v0, v0, v135
	v_exp_f32_e32 v137, v137
	v_add_f32_e32 v0, v0, v136
	v_exp_f32_e32 v138, v138
	v_add_f32_e32 v0, v0, v137
	v_exp_f32_e32 v139, v139
	v_add_f32_e32 v0, v0, v138
	v_exp_f32_e32 v140, v140
	v_add_f32_e32 v0, v0, v139
	v_exp_f32_e32 v141, v141
	v_add_f32_e32 v0, v0, v140
	v_exp_f32_e32 v142, v142
	v_add_f32_e32 v0, v0, v141
	v_exp_f32_e32 v143, v143
	v_add_f32_e32 v0, v0, v142
	v_exp_f32_e32 v144, v144
	v_add_f32_e32 v0, v0, v143
	v_exp_f32_e32 v145, v145
	v_add_f32_e32 v0, v0, v144
	v_cvt_pk_bf16_f32 v130, v130, v131
	v_cvt_pk_bf16_f32 v131, v132, v133
	v_cvt_pk_bf16_f32 v132, v134, v135
	v_cvt_pk_bf16_f32 v133, v136, v137
	v_cvt_pk_bf16_f32 v134, v138, v139
	v_cvt_pk_bf16_f32 v135, v140, v141
	v_cvt_pk_bf16_f32 v136, v142, v143
	v_add_f32_e32 v0, v0, v145
	v_cvt_pk_bf16_f32 v137, v144, v145
	v_add_f32_e32 v232, v232, v0
	v_exp_f32_e32 v146, v146
	v_exp_f32_e32 v147, v147
	v_exp_f32_e32 v148, v148
	v_add_f32_e32 v0, v146, v147
	v_exp_f32_e32 v149, v149
	v_add_f32_e32 v0, v0, v148
	v_exp_f32_e32 v150, v150
	v_add_f32_e32 v0, v0, v149
	v_exp_f32_e32 v151, v151
	v_add_f32_e32 v0, v0, v150
	v_exp_f32_e32 v152, v152
	v_add_f32_e32 v0, v0, v151
	v_exp_f32_e32 v153, v153
	v_add_f32_e32 v0, v0, v152
	v_exp_f32_e32 v154, v154
	v_add_f32_e32 v0, v0, v153
	v_exp_f32_e32 v155, v155
	v_add_f32_e32 v0, v0, v154
	v_exp_f32_e32 v156, v156
	v_add_f32_e32 v0, v0, v155
	v_exp_f32_e32 v157, v157
	v_add_f32_e32 v0, v0, v156
	v_exp_f32_e32 v158, v158
	v_add_f32_e32 v0, v0, v157
	v_exp_f32_e32 v159, v159
	v_add_f32_e32 v0, v0, v158
	v_exp_f32_e32 v160, v160
	v_add_f32_e32 v0, v0, v159
	v_exp_f32_e32 v161, v161
	v_add_f32_e32 v0, v0, v160
	v_cvt_pk_bf16_f32 v146, v146, v147
	v_cvt_pk_bf16_f32 v147, v148, v149
	v_cvt_pk_bf16_f32 v148, v150, v151
	v_cvt_pk_bf16_f32 v149, v152, v153
	v_cvt_pk_bf16_f32 v150, v154, v155
	v_cvt_pk_bf16_f32 v151, v156, v157
	v_cvt_pk_bf16_f32 v152, v158, v159
	v_add_f32_e32 v0, v0, v161
	v_cvt_pk_bf16_f32 v153, v160, v161
	v_add_f32_e32 v244, v244, v0
	s_waitcnt lgkmcnt(6)
	v_mfma_f32_16x16x32_bf16 v[114:117], v[162:165], v[130:133], v[114:117]
	v_mfma_f32_16x16x32_bf16 v[122:125], v[162:165], v[146:149], v[122:125]
	ds_read_b64_tr_b16 v[162:163], v242 offset:512
	ds_read_b64_tr_b16 v[164:165], v242 offset:8704
	s_waitcnt lgkmcnt(6)
	v_mfma_f32_16x16x32_bf16 v[114:117], v[166:169], v[134:137], v[114:117]
	v_mfma_f32_16x16x32_bf16 v[122:125], v[166:169], v[150:153], v[122:125]
	ds_read_b64_tr_b16 v[166:167], v242 offset:16896
	ds_read_b64_tr_b16 v[168:169], v242 offset:25088
	s_waitcnt lgkmcnt(6)
	v_mfma_f32_16x16x32_bf16 v[118:121], v[170:173], v[130:133], v[118:121]
	v_mfma_f32_16x16x32_bf16 v[126:129], v[170:173], v[146:149], v[126:129]
	ds_read_b64_tr_b16 v[170:171], v242 offset:768
	ds_read_b64_tr_b16 v[172:173], v242 offset:8960
	s_waitcnt lgkmcnt(6)
	v_mfma_f32_16x16x32_bf16 v[118:121], v[174:177], v[134:137], v[118:121]
	v_mfma_f32_16x16x32_bf16 v[126:129], v[174:177], v[150:153], v[126:129]
	ds_read_b64_tr_b16 v[174:175], v242 offset:17152
	ds_read_b64_tr_b16 v[176:177], v242 offset:25344
	s_waitcnt lgkmcnt(6)
	v_mfma_f32_16x16x32_bf16 v[98:101], v[162:165], v[130:133], v[98:101]
	v_mfma_f32_16x16x32_bf16 v[106:109], v[162:165], v[146:149], v[106:109]
	ds_read_b64_tr_b16 v[162:163], v242 offset:1024
	ds_read_b64_tr_b16 v[164:165], v242 offset:9216
	s_waitcnt lgkmcnt(6)
	v_mfma_f32_16x16x32_bf16 v[98:101], v[166:169], v[134:137], v[98:101]
	v_mfma_f32_16x16x32_bf16 v[106:109], v[166:169], v[150:153], v[106:109]
	ds_read_b64_tr_b16 v[166:167], v242 offset:17408
	ds_read_b64_tr_b16 v[168:169], v242 offset:25600
	s_waitcnt lgkmcnt(6)
	v_mfma_f32_16x16x32_bf16 v[102:105], v[170:173], v[130:133], v[102:105]
	v_mfma_f32_16x16x32_bf16 v[110:113], v[170:173], v[146:149], v[110:113]
	ds_read_b64_tr_b16 v[170:171], v242 offset:1280
	ds_read_b64_tr_b16 v[172:173], v242 offset:9472
	s_waitcnt lgkmcnt(6)
	v_mfma_f32_16x16x32_bf16 v[102:105], v[174:177], v[134:137], v[102:105]
	v_mfma_f32_16x16x32_bf16 v[110:113], v[174:177], v[150:153], v[110:113]
	ds_read_b64_tr_b16 v[174:175], v242 offset:17664
	ds_read_b64_tr_b16 v[176:177], v242 offset:25856
	s_waitcnt lgkmcnt(6)
	v_mfma_f32_16x16x32_bf16 v[82:85], v[162:165], v[130:133], v[82:85]
	v_mfma_f32_16x16x32_bf16 v[90:93], v[162:165], v[146:149], v[90:93]
	ds_read_b64_tr_b16 v[162:163], v242 offset:1536
	ds_read_b64_tr_b16 v[164:165], v242 offset:9728
	s_waitcnt lgkmcnt(6)
	v_mfma_f32_16x16x32_bf16 v[82:85], v[166:169], v[134:137], v[82:85]
	v_mfma_f32_16x16x32_bf16 v[90:93], v[166:169], v[150:153], v[90:93]
	ds_read_b64_tr_b16 v[166:167], v242 offset:17920
	ds_read_b64_tr_b16 v[168:169], v242 offset:26112
	s_waitcnt lgkmcnt(6)
	v_mfma_f32_16x16x32_bf16 v[86:89], v[170:173], v[130:133], v[86:89]
	v_mfma_f32_16x16x32_bf16 v[94:97], v[170:173], v[146:149], v[94:97]
	ds_read_b64_tr_b16 v[170:171], v242 offset:1792
	ds_read_b64_tr_b16 v[172:173], v242 offset:9984
	s_waitcnt lgkmcnt(6)
	v_mfma_f32_16x16x32_bf16 v[86:89], v[174:177], v[134:137], v[86:89]
	v_mfma_f32_16x16x32_bf16 v[94:97], v[174:177], v[150:153], v[94:97]
	ds_read_b64_tr_b16 v[174:175], v242 offset:18176
	ds_read_b64_tr_b16 v[176:177], v242 offset:26368
	s_waitcnt lgkmcnt(6)
	v_mfma_f32_16x16x32_bf16 v[66:69], v[162:165], v[130:133], v[66:69]
	v_mfma_f32_16x16x32_bf16 v[74:77], v[162:165], v[146:149], v[74:77]
	ds_read_b64_tr_b16 v[162:163], v242 offset:2048
	ds_read_b64_tr_b16 v[164:165], v242 offset:10240
	s_waitcnt lgkmcnt(6)
	v_mfma_f32_16x16x32_bf16 v[66:69], v[166:169], v[134:137], v[66:69]
	v_mfma_f32_16x16x32_bf16 v[74:77], v[166:169], v[150:153], v[74:77]
	ds_read_b64_tr_b16 v[166:167], v242 offset:18432
	ds_read_b64_tr_b16 v[168:169], v242 offset:26624
	s_waitcnt lgkmcnt(6)
	v_mfma_f32_16x16x32_bf16 v[70:73], v[170:173], v[130:133], v[70:73]
	v_mfma_f32_16x16x32_bf16 v[78:81], v[170:173], v[146:149], v[78:81]
	ds_read_b64_tr_b16 v[170:171], v242 offset:2304
	ds_read_b64_tr_b16 v[172:173], v242 offset:10496
	s_waitcnt lgkmcnt(6)
	v_mfma_f32_16x16x32_bf16 v[70:73], v[174:177], v[134:137], v[70:73]
	v_mfma_f32_16x16x32_bf16 v[78:81], v[174:177], v[150:153], v[78:81]
	ds_read_b64_tr_b16 v[174:175], v242 offset:18688
	ds_read_b64_tr_b16 v[176:177], v242 offset:26880
	s_waitcnt lgkmcnt(6)
	v_mfma_f32_16x16x32_bf16 v[50:53], v[162:165], v[130:133], v[50:53]
	v_mfma_f32_16x16x32_bf16 v[58:61], v[162:165], v[146:149], v[58:61]
	ds_read_b64_tr_b16 v[162:163], v242 offset:2560
	ds_read_b64_tr_b16 v[164:165], v242 offset:10752
	s_waitcnt lgkmcnt(6)
	v_mfma_f32_16x16x32_bf16 v[50:53], v[166:169], v[134:137], v[50:53]
	v_mfma_f32_16x16x32_bf16 v[58:61], v[166:169], v[150:153], v[58:61]
	ds_read_b64_tr_b16 v[166:167], v242 offset:18944
	ds_read_b64_tr_b16 v[168:169], v242 offset:27136
	s_waitcnt lgkmcnt(6)
	v_mfma_f32_16x16x32_bf16 v[54:57], v[170:173], v[130:133], v[54:57]
	v_mfma_f32_16x16x32_bf16 v[62:65], v[170:173], v[146:149], v[62:65]
	ds_read_b64_tr_b16 v[170:171], v242 offset:2816
	ds_read_b64_tr_b16 v[172:173], v242 offset:11008
	s_waitcnt lgkmcnt(6)
	v_mfma_f32_16x16x32_bf16 v[54:57], v[174:177], v[134:137], v[54:57]
	v_mfma_f32_16x16x32_bf16 v[62:65], v[174:177], v[150:153], v[62:65]
	ds_read_b64_tr_b16 v[174:175], v242 offset:19200
	ds_read_b64_tr_b16 v[176:177], v242 offset:27392
	s_waitcnt lgkmcnt(6)
	v_mfma_f32_16x16x32_bf16 v[34:37], v[162:165], v[130:133], v[34:37]
	v_mfma_f32_16x16x32_bf16 v[42:45], v[162:165], v[146:149], v[42:45]
	ds_read_b64_tr_b16 v[162:163], v242 offset:3072
	ds_read_b64_tr_b16 v[164:165], v242 offset:11264
	s_waitcnt lgkmcnt(6)
	v_mfma_f32_16x16x32_bf16 v[34:37], v[166:169], v[134:137], v[34:37]
	v_mfma_f32_16x16x32_bf16 v[42:45], v[166:169], v[150:153], v[42:45]
	ds_read_b64_tr_b16 v[166:167], v242 offset:19456
	ds_read_b64_tr_b16 v[168:169], v242 offset:27648
	s_waitcnt lgkmcnt(6)
	v_mfma_f32_16x16x32_bf16 v[38:41], v[170:173], v[130:133], v[38:41]
	v_mfma_f32_16x16x32_bf16 v[46:49], v[170:173], v[146:149], v[46:49]
	ds_read_b64_tr_b16 v[170:171], v242 offset:3328
	ds_read_b64_tr_b16 v[172:173], v242 offset:11520
	s_waitcnt lgkmcnt(6)
	v_mfma_f32_16x16x32_bf16 v[38:41], v[174:177], v[134:137], v[38:41]
	v_mfma_f32_16x16x32_bf16 v[46:49], v[174:177], v[150:153], v[46:49]
	ds_read_b64_tr_b16 v[174:175], v242 offset:19712
	ds_read_b64_tr_b16 v[176:177], v242 offset:27904
	s_waitcnt lgkmcnt(6)
	v_mfma_f32_16x16x32_bf16 v[18:21], v[162:165], v[130:133], v[18:21]
	v_mfma_f32_16x16x32_bf16 v[26:29], v[162:165], v[146:149], v[26:29]
	ds_read_b64_tr_b16 v[162:163], v242 offset:3584
	ds_read_b64_tr_b16 v[164:165], v242 offset:11776
	s_waitcnt lgkmcnt(6)
	v_mfma_f32_16x16x32_bf16 v[18:21], v[166:169], v[134:137], v[18:21]
	v_mfma_f32_16x16x32_bf16 v[26:29], v[166:169], v[150:153], v[26:29]
	ds_read_b64_tr_b16 v[166:167], v242 offset:19968
	ds_read_b64_tr_b16 v[168:169], v242 offset:28160
	s_waitcnt lgkmcnt(6)
	v_mfma_f32_16x16x32_bf16 v[22:25], v[170:173], v[130:133], v[22:25]
	v_mfma_f32_16x16x32_bf16 v[30:33], v[170:173], v[146:149], v[30:33]
	ds_read_b64_tr_b16 v[170:171], v242 offset:3840
	ds_read_b64_tr_b16 v[172:173], v242 offset:12032
	s_waitcnt lgkmcnt(6)
	v_mfma_f32_16x16x32_bf16 v[22:25], v[174:177], v[134:137], v[22:25]
	v_mfma_f32_16x16x32_bf16 v[30:33], v[174:177], v[150:153], v[30:33]
	ds_read_b64_tr_b16 v[174:175], v242 offset:20224
	ds_read_b64_tr_b16 v[176:177], v242 offset:28416
	s_waitcnt lgkmcnt(6)
	v_mfma_f32_16x16x32_bf16 v[2:5], v[162:165], v[130:133], v[2:5]
	v_mfma_f32_16x16x32_bf16 v[10:13], v[162:165], v[146:149], v[10:13]
	s_waitcnt lgkmcnt(4)
	v_mfma_f32_16x16x32_bf16 v[2:5], v[166:169], v[134:137], v[2:5]
	v_mfma_f32_16x16x32_bf16 v[10:13], v[166:169], v[150:153], v[10:13]
	s_waitcnt lgkmcnt(2)
	v_mfma_f32_16x16x32_bf16 v[6:9], v[170:173], v[130:133], v[6:9]
	v_mfma_f32_16x16x32_bf16 v[14:17], v[170:173], v[146:149], v[14:17]
	s_waitcnt lgkmcnt(0)
	v_mfma_f32_16x16x32_bf16 v[6:9], v[174:177], v[134:137], v[6:9]
	v_mfma_f32_16x16x32_bf16 v[14:17], v[174:177], v[150:153], v[14:17]
	s_xor_b32 s4, s70, 0x10000
	v_xor_b32_e32 v234, s4, v221
	v_xor_b32_e32 v235, 64, v234
	v_xor_b32_e32 v236, 0x80, v234
	v_xor_b32_e32 v237, 0xc0, v234
	s_branch .Lat_end_a
.Lat_resc_a:
	s_nop 1
	v_permlane16_swap_b32_e32 v238, v239
	v_max_f32_e32 v238, v238, v239
	v_mov_b32_e32 v239, v238
	s_nop 1
	v_permlane32_swap_b32_e32 v238, v239
	v_max_f32_e32 v238, v238, v239
	v_mov_b32_e32 v239, v238
	s_nop 1
	v_permlane16_swap_b32_e32 v238, v239
	v_max_f32_e32 v240, s94, v238
	v_max_f32_e32 v241, 0, v240
	v_exp_f32_e64 v241, -v241
	v_sub_f32_e32 v246, v246, v240
	v_mul_f32_e32 v232, v232, v241
	v_sub_f32_e32 v247, v247, v240
	v_sub_f32_e32 v248, v248, v240
	v_sub_f32_e32 v249, v249, v240
	v_sub_f32_e32 v130, v130, v240
	v_sub_f32_e32 v131, v131, v240
	v_sub_f32_e32 v132, v132, v240
	v_sub_f32_e32 v133, v133, v240
	v_sub_f32_e32 v134, v134, v240
	v_sub_f32_e32 v135, v135, v240
	v_sub_f32_e32 v136, v136, v240
	v_sub_f32_e32 v137, v137, v240
	v_sub_f32_e32 v138, v138, v240
	v_sub_f32_e32 v139, v139, v240
	v_sub_f32_e32 v140, v140, v240
	v_sub_f32_e32 v141, v141, v240
	v_sub_f32_e32 v142, v142, v240
	v_sub_f32_e32 v143, v143, v240
	v_sub_f32_e32 v144, v144, v240
	v_sub_f32_e32 v145, v145, v240
	v_mul_f32_e32 v114, v114, v241
	v_mul_f32_e32 v115, v115, v241
	v_mul_f32_e32 v116, v116, v241
	v_mul_f32_e32 v117, v117, v241
	v_mul_f32_e32 v118, v118, v241
	v_mul_f32_e32 v119, v119, v241
	v_mul_f32_e32 v120, v120, v241
	v_mul_f32_e32 v121, v121, v241
	v_mul_f32_e32 v98, v98, v241
	v_mul_f32_e32 v99, v99, v241
	v_mul_f32_e32 v100, v100, v241
	v_mul_f32_e32 v101, v101, v241
	v_mul_f32_e32 v102, v102, v241
	v_mul_f32_e32 v103, v103, v241
	v_mul_f32_e32 v104, v104, v241
	v_mul_f32_e32 v105, v105, v241
	v_mul_f32_e32 v82, v82, v241
	v_mul_f32_e32 v83, v83, v241
	v_mul_f32_e32 v84, v84, v241
	v_mul_f32_e32 v85, v85, v241
	v_mul_f32_e32 v86, v86, v241
	v_mul_f32_e32 v87, v87, v241
	v_mul_f32_e32 v88, v88, v241
	v_mul_f32_e32 v89, v89, v241
	v_mul_f32_e32 v66, v66, v241
	v_mul_f32_e32 v67, v67, v241
	v_mul_f32_e32 v68, v68, v241
	v_mul_f32_e32 v69, v69, v241
	v_mul_f32_e32 v70, v70, v241
	v_mul_f32_e32 v71, v71, v241
	v_mul_f32_e32 v72, v72, v241
	v_mul_f32_e32 v73, v73, v241
	v_mul_f32_e32 v50, v50, v241
	v_mul_f32_e32 v51, v51, v241
	v_mul_f32_e32 v52, v52, v241
	v_mul_f32_e32 v53, v53, v241
	v_mul_f32_e32 v54, v54, v241
	v_mul_f32_e32 v55, v55, v241
	v_mul_f32_e32 v56, v56, v241
	v_mul_f32_e32 v57, v57, v241
	v_mul_f32_e32 v34, v34, v241
	v_mul_f32_e32 v35, v35, v241
	v_mul_f32_e32 v36, v36, v241
	v_mul_f32_e32 v37, v37, v241
	v_mul_f32_e32 v38, v38, v241
	v_mul_f32_e32 v39, v39, v241
	v_mul_f32_e32 v40, v40, v241
	v_mul_f32_e32 v41, v41, v241
	v_mul_f32_e32 v18, v18, v241
	v_mul_f32_e32 v19, v19, v241
	v_mul_f32_e32 v20, v20, v241
	v_mul_f32_e32 v21, v21, v241
	v_mul_f32_e32 v22, v22, v241
	v_mul_f32_e32 v23, v23, v241
	v_mul_f32_e32 v24, v24, v241
	v_mul_f32_e32 v25, v25, v241
	v_mul_f32_e32 v2, v2, v241
	v_mul_f32_e32 v3, v3, v241
	v_mul_f32_e32 v4, v4, v241
	v_mul_f32_e32 v5, v5, v241
	v_mul_f32_e32 v6, v6, v241
	v_mul_f32_e32 v7, v7, v241
	v_mul_f32_e32 v8, v8, v241
	v_mul_f32_e32 v9, v9, v241
	v_max_f32_e32 v240, s94, v239
	v_max_f32_e32 v241, 0, v240
	v_exp_f32_e64 v241, -v241
	v_sub_f32_e32 v250, v250, v240
	v_mul_f32_e32 v244, v244, v241
	v_sub_f32_e32 v251, v251, v240
	v_sub_f32_e32 v252, v252, v240
	v_sub_f32_e32 v253, v253, v240
	v_sub_f32_e32 v146, v146, v240
	v_sub_f32_e32 v147, v147, v240
	v_sub_f32_e32 v148, v148, v240
	v_sub_f32_e32 v149, v149, v240
	v_sub_f32_e32 v150, v150, v240
	v_sub_f32_e32 v151, v151, v240
	v_sub_f32_e32 v152, v152, v240
	v_sub_f32_e32 v153, v153, v240
	v_sub_f32_e32 v154, v154, v240
	v_sub_f32_e32 v155, v155, v240
	v_sub_f32_e32 v156, v156, v240
	v_sub_f32_e32 v157, v157, v240
	v_sub_f32_e32 v158, v158, v240
	v_sub_f32_e32 v159, v159, v240
	v_sub_f32_e32 v160, v160, v240
	v_sub_f32_e32 v161, v161, v240
	v_mul_f32_e32 v122, v122, v241
	v_mul_f32_e32 v123, v123, v241
	v_mul_f32_e32 v124, v124, v241
	v_mul_f32_e32 v125, v125, v241
	v_mul_f32_e32 v126, v126, v241
	v_mul_f32_e32 v127, v127, v241
	v_mul_f32_e32 v128, v128, v241
	v_mul_f32_e32 v129, v129, v241
	v_mul_f32_e32 v106, v106, v241
	v_mul_f32_e32 v107, v107, v241
	v_mul_f32_e32 v108, v108, v241
	v_mul_f32_e32 v109, v109, v241
	v_mul_f32_e32 v110, v110, v241
	v_mul_f32_e32 v111, v111, v241
	v_mul_f32_e32 v112, v112, v241
	v_mul_f32_e32 v113, v113, v241
	v_mul_f32_e32 v90, v90, v241
	v_mul_f32_e32 v91, v91, v241
	v_mul_f32_e32 v92, v92, v241
	v_mul_f32_e32 v93, v93, v241
	v_mul_f32_e32 v94, v94, v241
	v_mul_f32_e32 v95, v95, v241
	v_mul_f32_e32 v96, v96, v241
	v_mul_f32_e32 v97, v97, v241
	v_mul_f32_e32 v74, v74, v241
	v_mul_f32_e32 v75, v75, v241
	v_mul_f32_e32 v76, v76, v241
	v_mul_f32_e32 v77, v77, v241
	v_mul_f32_e32 v78, v78, v241
	v_mul_f32_e32 v79, v79, v241
	v_mul_f32_e32 v80, v80, v241
	v_mul_f32_e32 v81, v81, v241
	v_mul_f32_e32 v58, v58, v241
	v_mul_f32_e32 v59, v59, v241
	v_mul_f32_e32 v60, v60, v241
	v_mul_f32_e32 v61, v61, v241
	v_mul_f32_e32 v62, v62, v241
	v_mul_f32_e32 v63, v63, v241
	v_mul_f32_e32 v64, v64, v241
	v_mul_f32_e32 v65, v65, v241
	v_mul_f32_e32 v42, v42, v241
	v_mul_f32_e32 v43, v43, v241
	v_mul_f32_e32 v44, v44, v241
	v_mul_f32_e32 v45, v45, v241
	v_mul_f32_e32 v46, v46, v241
	v_mul_f32_e32 v47, v47, v241
	v_mul_f32_e32 v48, v48, v241
	v_mul_f32_e32 v49, v49, v241
	v_mul_f32_e32 v26, v26, v241
	v_mul_f32_e32 v27, v27, v241
	v_mul_f32_e32 v28, v28, v241
	v_mul_f32_e32 v29, v29, v241
	v_mul_f32_e32 v30, v30, v241
	v_mul_f32_e32 v31, v31, v241
	v_mul_f32_e32 v32, v32, v241
	v_mul_f32_e32 v33, v33, v241
	v_mul_f32_e32 v10, v10, v241
	v_mul_f32_e32 v11, v11, v241
	v_mul_f32_e32 v12, v12, v241
	v_mul_f32_e32 v13, v13, v241
	v_mul_f32_e32 v14, v14, v241
	v_mul_f32_e32 v15, v15, v241
	v_mul_f32_e32 v16, v16, v241
	v_mul_f32_e32 v17, v17, v241
	s_branch .Lat_exp_a
.Lat_diag_a:
	s_nop 7
	v_subrev_u32_e32 v234, 0, v223
	v_cmp_gt_i32_e64 s[4:5], 0, v234
	v_med3_i32 v234, v234, 0, s81
	v_lshl_add_u32 v234, v234, 2, s80
	ds_read_b32 v238, v234
	v_subrev_u32_e32 v235, 1, v223
	v_cmp_gt_i32_e64 s[6:7], 0, v235
	v_med3_i32 v235, v235, 0, s81
	v_lshl_add_u32 v235, v235, 2, s80
	ds_read_b32 v239, v235
	v_subrev_u32_e32 v236, 2, v223
	v_cmp_gt_i32_e64 s[8:9], 0, v236
	v_med3_i32 v236, v236, 0, s81
	v_lshl_add_u32 v236, v236, 2, s80
	ds_read_b32 v240, v236
	v_subrev_u32_e32 v237, 3, v223
	v_cmp_gt_i32_e64 s[10:11], 0, v237
	v_med3_i32 v237, v237, 0, s81
	v_lshl_add_u32 v237, v237, 2, s80
	ds_read_b32 v241, v237
	s_waitcnt lgkmcnt(0)
	v_add_f32_e32 v130, v130, v238
	v_cndmask_b32_e64 v130, v130, v216, s[4:5]
	v_add_f32_e32 v131, v131, v239
	v_cndmask_b32_e64 v131, v131, v216, s[6:7]
	v_add_f32_e32 v132, v132, v240
	v_cndmask_b32_e64 v132, v132, v216, s[8:9]
	v_add_f32_e32 v133, v133, v241
	v_cndmask_b32_e64 v133, v133, v216, s[10:11]
	v_subrev_u32_e32 v234, 16, v223
	v_cmp_gt_i32_e64 s[4:5], 0, v234
	v_med3_i32 v234, v234, 0, s81
	v_lshl_add_u32 v234, v234, 2, s80
	ds_read_b32 v238, v234
	v_subrev_u32_e32 v235, 17, v223
	v_cmp_gt_i32_e64 s[6:7], 0, v235
	v_med3_i32 v235, v235, 0, s81
	v_lshl_add_u32 v235, v235, 2, s80
	ds_read_b32 v239, v235
	v_subrev_u32_e32 v236, 18, v223
	v_cmp_gt_i32_e64 s[8:9], 0, v236
	v_med3_i32 v236, v236, 0, s81
	v_lshl_add_u32 v236, v236, 2, s80
	ds_read_b32 v240, v236
	v_subrev_u32_e32 v237, 19, v223
	v_cmp_gt_i32_e64 s[10:11], 0, v237
	v_med3_i32 v237, v237, 0, s81
	v_lshl_add_u32 v237, v237, 2, s80
	ds_read_b32 v241, v237
	s_waitcnt lgkmcnt(0)
	v_add_f32_e32 v134, v134, v238
	v_cndmask_b32_e64 v134, v134, v216, s[4:5]
	v_add_f32_e32 v135, v135, v239
	v_cndmask_b32_e64 v135, v135, v216, s[6:7]
	v_add_f32_e32 v136, v136, v240
	v_cndmask_b32_e64 v136, v136, v216, s[8:9]
	v_add_f32_e32 v137, v137, v241
	v_cndmask_b32_e64 v137, v137, v216, s[10:11]
	v_subrev_u32_e32 v234, 32, v223
	v_cmp_gt_i32_e64 s[4:5], 0, v234
	v_med3_i32 v234, v234, 0, s81
	v_lshl_add_u32 v234, v234, 2, s80
	ds_read_b32 v238, v234
	v_subrev_u32_e32 v235, 33, v223
	v_cmp_gt_i32_e64 s[6:7], 0, v235
	v_med3_i32 v235, v235, 0, s81
	v_lshl_add_u32 v235, v235, 2, s80
	ds_read_b32 v239, v235
	v_subrev_u32_e32 v236, 34, v223
	v_cmp_gt_i32_e64 s[8:9], 0, v236
	v_med3_i32 v236, v236, 0, s81
	v_lshl_add_u32 v236, v236, 2, s80
	ds_read_b32 v240, v236
	v_subrev_u32_e32 v237, 35, v223
	v_cmp_gt_i32_e64 s[10:11], 0, v237
	v_med3_i32 v237, v237, 0, s81
	v_lshl_add_u32 v237, v237, 2, s80
	ds_read_b32 v241, v237
	s_waitcnt lgkmcnt(0)
	v_add_f32_e32 v138, v138, v238
	v_cndmask_b32_e64 v138, v138, v216, s[4:5]
	v_add_f32_e32 v139, v139, v239
	v_cndmask_b32_e64 v139, v139, v216, s[6:7]
	v_add_f32_e32 v140, v140, v240
	v_cndmask_b32_e64 v140, v140, v216, s[8:9]
	v_add_f32_e32 v141, v141, v241
	v_cndmask_b32_e64 v141, v141, v216, s[10:11]
	v_subrev_u32_e32 v234, 48, v223
	v_cmp_gt_i32_e64 s[4:5], 0, v234
	v_med3_i32 v234, v234, 0, s81
	v_lshl_add_u32 v234, v234, 2, s80
	ds_read_b32 v238, v234
	v_subrev_u32_e32 v235, 49, v223
	v_cmp_gt_i32_e64 s[6:7], 0, v235
	v_med3_i32 v235, v235, 0, s81
	v_lshl_add_u32 v235, v235, 2, s80
	ds_read_b32 v239, v235
	v_subrev_u32_e32 v236, 50, v223
	v_cmp_gt_i32_e64 s[8:9], 0, v236
	v_med3_i32 v236, v236, 0, s81
	v_lshl_add_u32 v236, v236, 2, s80
	ds_read_b32 v240, v236
	v_subrev_u32_e32 v237, 51, v223
	v_cmp_gt_i32_e64 s[10:11], 0, v237
	v_med3_i32 v237, v237, 0, s81
	v_lshl_add_u32 v237, v237, 2, s80
	ds_read_b32 v241, v237
	s_waitcnt lgkmcnt(0)
	v_add_f32_e32 v142, v142, v238
	v_cndmask_b32_e64 v142, v142, v216, s[4:5]
	v_add_f32_e32 v143, v143, v239
	v_cndmask_b32_e64 v143, v143, v216, s[6:7]
	v_add_f32_e32 v144, v144, v240
	v_cndmask_b32_e64 v144, v144, v216, s[8:9]
	v_add_f32_e32 v145, v145, v241
	v_cndmask_b32_e64 v145, v145, v216, s[10:11]
	v_subrev_u32_e32 v234, -16, v223
	v_cmp_gt_i32_e64 s[4:5], 0, v234
	v_med3_i32 v234, v234, 0, s81
	v_lshl_add_u32 v234, v234, 2, s80
	ds_read_b32 v238, v234
	v_subrev_u32_e32 v235, -15, v223
	v_cmp_gt_i32_e64 s[6:7], 0, v235
	v_med3_i32 v235, v235, 0, s81
	v_lshl_add_u32 v235, v235, 2, s80
	ds_read_b32 v239, v235
	v_subrev_u32_e32 v236, -14, v223
	v_cmp_gt_i32_e64 s[8:9], 0, v236
	v_med3_i32 v236, v236, 0, s81
	v_lshl_add_u32 v236, v236, 2, s80
	ds_read_b32 v240, v236
	v_subrev_u32_e32 v237, -13, v223
	v_cmp_gt_i32_e64 s[10:11], 0, v237
	v_med3_i32 v237, v237, 0, s81
	v_lshl_add_u32 v237, v237, 2, s80
	ds_read_b32 v241, v237
	s_waitcnt lgkmcnt(0)
	v_add_f32_e32 v146, v146, v238
	v_cndmask_b32_e64 v146, v146, v216, s[4:5]
	v_add_f32_e32 v147, v147, v239
	v_cndmask_b32_e64 v147, v147, v216, s[6:7]
	v_add_f32_e32 v148, v148, v240
	v_cndmask_b32_e64 v148, v148, v216, s[8:9]
	v_add_f32_e32 v149, v149, v241
	v_cndmask_b32_e64 v149, v149, v216, s[10:11]
	v_subrev_u32_e32 v234, 0, v223
	v_cmp_gt_i32_e64 s[4:5], 0, v234
	v_med3_i32 v234, v234, 0, s81
	v_lshl_add_u32 v234, v234, 2, s80
	ds_read_b32 v238, v234
	v_subrev_u32_e32 v235, 1, v223
	v_cmp_gt_i32_e64 s[6:7], 0, v235
	v_med3_i32 v235, v235, 0, s81
	v_lshl_add_u32 v235, v235, 2, s80
	ds_read_b32 v239, v235
	v_subrev_u32_e32 v236, 2, v223
	v_cmp_gt_i32_e64 s[8:9], 0, v236
	v_med3_i32 v236, v236, 0, s81
	v_lshl_add_u32 v236, v236, 2, s80
	ds_read_b32 v240, v236
	v_subrev_u32_e32 v237, 3, v223
	v_cmp_gt_i32_e64 s[10:11], 0, v237
	v_med3_i32 v237, v237, 0, s81
	v_lshl_add_u32 v237, v237, 2, s80
	ds_read_b32 v241, v237
	s_waitcnt lgkmcnt(0)
	v_add_f32_e32 v150, v150, v238
	v_cndmask_b32_e64 v150, v150, v216, s[4:5]
	v_add_f32_e32 v151, v151, v239
	v_cndmask_b32_e64 v151, v151, v216, s[6:7]
	v_add_f32_e32 v152, v152, v240
	v_cndmask_b32_e64 v152, v152, v216, s[8:9]
	v_add_f32_e32 v153, v153, v241
	v_cndmask_b32_e64 v153, v153, v216, s[10:11]
	v_subrev_u32_e32 v234, 16, v223
	v_cmp_gt_i32_e64 s[4:5], 0, v234
	v_med3_i32 v234, v234, 0, s81
	v_lshl_add_u32 v234, v234, 2, s80
	ds_read_b32 v238, v234
	v_subrev_u32_e32 v235, 17, v223
	v_cmp_gt_i32_e64 s[6:7], 0, v235
	v_med3_i32 v235, v235, 0, s81
	v_lshl_add_u32 v235, v235, 2, s80
	ds_read_b32 v239, v235
	v_subrev_u32_e32 v236, 18, v223
	v_cmp_gt_i32_e64 s[8:9], 0, v236
	v_med3_i32 v236, v236, 0, s81
	v_lshl_add_u32 v236, v236, 2, s80
	ds_read_b32 v240, v236
	v_subrev_u32_e32 v237, 19, v223
	v_cmp_gt_i32_e64 s[10:11], 0, v237
	v_med3_i32 v237, v237, 0, s81
	v_lshl_add_u32 v237, v237, 2, s80
	ds_read_b32 v241, v237
	s_waitcnt lgkmcnt(0)
	v_add_f32_e32 v154, v154, v238
	v_cndmask_b32_e64 v154, v154, v216, s[4:5]
	v_add_f32_e32 v155, v155, v239
	v_cndmask_b32_e64 v155, v155, v216, s[6:7]
	v_add_f32_e32 v156, v156, v240
	v_cndmask_b32_e64 v156, v156, v216, s[8:9]
	v_add_f32_e32 v157, v157, v241
	v_cndmask_b32_e64 v157, v157, v216, s[10:11]
	v_subrev_u32_e32 v234, 32, v223
	v_cmp_gt_i32_e64 s[4:5], 0, v234
	v_med3_i32 v234, v234, 0, s81
	v_lshl_add_u32 v234, v234, 2, s80
	ds_read_b32 v238, v234
	v_subrev_u32_e32 v235, 33, v223
	v_cmp_gt_i32_e64 s[6:7], 0, v235
	v_med3_i32 v235, v235, 0, s81
	v_lshl_add_u32 v235, v235, 2, s80
	ds_read_b32 v239, v235
	v_subrev_u32_e32 v236, 34, v223
	v_cmp_gt_i32_e64 s[8:9], 0, v236
	v_med3_i32 v236, v236, 0, s81
	v_lshl_add_u32 v236, v236, 2, s80
	ds_read_b32 v240, v236
	v_subrev_u32_e32 v237, 35, v223
	v_cmp_gt_i32_e64 s[10:11], 0, v237
	v_med3_i32 v237, v237, 0, s81
	v_lshl_add_u32 v237, v237, 2, s80
	ds_read_b32 v241, v237
	s_waitcnt lgkmcnt(0)
	v_add_f32_e32 v158, v158, v238
	v_cndmask_b32_e64 v158, v158, v216, s[4:5]
	v_add_f32_e32 v159, v159, v239
	v_cndmask_b32_e64 v159, v159, v216, s[6:7]
	v_add_f32_e32 v160, v160, v240
	v_cndmask_b32_e64 v160, v160, v216, s[8:9]
	v_add_f32_e32 v161, v161, v241
	v_cndmask_b32_e64 v161, v161, v216, s[10:11]
	s_branch .Lat_sm_a
.Lat_end_a:
.Lat_next:
	s_add_i32 s58, s58, 1
	s_xor_b32 s70, s70, 0x10000
	s_xor_b32 s71, s71, 0x10000
	v_add_u32_e32 v223, 0xffffffc0, v223
	s_addk_i32 s91, 0x40
	s_add_u32 s50, s50, 0x80000
	s_addc_u32 s51, s51, 0
	s_mov_b32 s94, 0
	s_cmp_le_u32 s58, s88
	s_cbranch_scc1 .Lat_loop
	s_waitcnt vmcnt(0) lgkmcnt(0)
	s_barrier
	s_cmp_gt_u32 s58, s89
	s_cbranch_scc1 .Lat_done
	ds_read_b128 v[162:165], v234
	ds_read_b128 v[166:169], v235
	ds_read_b128 v[170:173], v236
	ds_read_b128 v[174:177], v237
	v_add_u32_e32 v242, s70, v222
	s_waitcnt lgkmcnt(3)
	v_mfma_f32_16x16x32_bf16 v[130:133], v[162:165], v[178:181], v[246:249]
	v_mfma_f32_16x16x32_bf16 v[146:149], v[162:165], v[194:197], v[250:253]
	ds_read_b128 v[162:165], v234 offset:4096
	s_waitcnt lgkmcnt(3)
	v_mfma_f32_16x16x32_bf16 v[130:133], v[166:169], v[182:185], v[130:133]
	v_mfma_f32_16x16x32_bf16 v[146:149], v[166:169], v[198:201], v[146:149]
	ds_read_b128 v[166:169], v235 offset:4096
	s_waitcnt lgkmcnt(3)
	v_mfma_f32_16x16x32_bf16 v[130:133], v[170:173], v[186:189], v[130:133]
	v_mfma_f32_16x16x32_bf16 v[146:149], v[170:173], v[202:205], v[146:149]
	ds_read_b128 v[170:173], v236 offset:4096
	s_waitcnt lgkmcnt(3)
	v_mfma_f32_16x16x32_bf16 v[130:133], v[174:177], v[190:193], v[130:133]
	v_mfma_f32_16x16x32_bf16 v[146:149], v[174:177], v[206:209], v[146:149]
	ds_read_b128 v[174:177], v237 offset:4096
	s_waitcnt lgkmcnt(3)
	v_mfma_f32_16x16x32_bf16 v[134:137], v[162:165], v[178:181], v[246:249]
	v_mfma_f32_16x16x32_bf16 v[150:153], v[162:165], v[194:197], v[250:253]
	ds_read_b128 v[162:165], v234 offset:8192
	s_waitcnt lgkmcnt(3)
	v_mfma_f32_16x16x32_bf16 v[134:137], v[166:169], v[182:185], v[134:137]
	v_mfma_f32_16x16x32_bf16 v[150:153], v[166:169], v[198:201], v[150:153]
	ds_read_b128 v[166:169], v235 offset:8192
	s_waitcnt lgkmcnt(3)
	v_mfma_f32_16x16x32_bf16 v[134:137], v[170:173], v[186:189], v[134:137]
	v_mfma_f32_16x16x32_bf16 v[150:153], v[170:173], v[202:205], v[150:153]
	ds_read_b128 v[170:173], v236 offset:8192
	s_waitcnt lgkmcnt(3)
	v_mfma_f32_16x16x32_bf16 v[134:137], v[174:177], v[190:193], v[134:137]
	v_mfma_f32_16x16x32_bf16 v[150:153], v[174:177], v[206:209], v[150:153]
	ds_read_b128 v[174:177], v237 offset:8192
	s_waitcnt lgkmcnt(3)
	v_mfma_f32_16x16x32_bf16 v[138:141], v[162:165], v[178:181], v[246:249]
	v_mfma_f32_16x16x32_bf16 v[154:157], v[162:165], v[194:197], v[250:253]
	ds_read_b128 v[162:165], v234 offset:12288
	s_waitcnt lgkmcnt(3)
	v_mfma_f32_16x16x32_bf16 v[138:141], v[166:169], v[182:185], v[138:141]
	v_mfma_f32_16x16x32_bf16 v[154:157], v[166:169], v[198:201], v[154:157]
	ds_read_b128 v[166:169], v235 offset:12288
	s_waitcnt lgkmcnt(3)
	v_mfma_f32_16x16x32_bf16 v[138:141], v[170:173], v[186:189], v[138:141]
	v_mfma_f32_16x16x32_bf16 v[154:157], v[170:173], v[202:205], v[154:157]
	ds_read_b128 v[170:173], v236 offset:12288
	s_waitcnt lgkmcnt(3)
	v_mfma_f32_16x16x32_bf16 v[138:141], v[174:177], v[190:193], v[138:141]
	v_mfma_f32_16x16x32_bf16 v[154:157], v[174:177], v[206:209], v[154:157]
	ds_read_b128 v[174:177], v237 offset:12288
	s_waitcnt lgkmcnt(3)
	v_mfma_f32_16x16x32_bf16 v[142:145], v[162:165], v[178:181], v[246:249]
	v_mfma_f32_16x16x32_bf16 v[158:161], v[162:165], v[194:197], v[250:253]
	ds_read_b64_tr_b16 v[162:163], v242 offset:0
	ds_read_b64_tr_b16 v[164:165], v242 offset:8192
	s_waitcnt lgkmcnt(4)
	v_mfma_f32_16x16x32_bf16 v[142:145], v[166:169], v[182:185], v[142:145]
	v_mfma_f32_16x16x32_bf16 v[158:161], v[166:169], v[198:201], v[158:161]
	ds_read_b64_tr_b16 v[166:167], v242 offset:16384
	ds_read_b64_tr_b16 v[168:169], v242 offset:24576
	s_waitcnt lgkmcnt(5)
	v_mfma_f32_16x16x32_bf16 v[142:145], v[170:173], v[186:189], v[142:145]
	v_mfma_f32_16x16x32_bf16 v[158:161], v[170:173], v[202:205], v[158:161]
	ds_read_b64_tr_b16 v[170:171], v242 offset:256
	ds_read_b64_tr_b16 v[172:173], v242 offset:8448
	s_waitcnt lgkmcnt(6)
	v_mfma_f32_16x16x32_bf16 v[142:145], v[174:177], v[190:193], v[142:145]
	v_mfma_f32_16x16x32_bf16 v[158:161], v[174:177], v[206:209], v[158:161]
	ds_read_b64_tr_b16 v[174:175], v242 offset:16640
	ds_read_b64_tr_b16 v[176:177], v242 offset:24832
	s_add_i32 s4, s91, 0xb0
	s_cmp_le_u32 s4, s3
	s_cbranch_scc0 .Lat_diag_b

.Lat_inactive:
	s_add_i32 m0, s71, 0x0
	s_nop 0
	global_load_lds_dwordx4 v231, s[50:51]
	s_add_i32 m0, s71, 0x400
	s_nop 0
	global_load_lds_dwordx4 v229, s[50:51]
	s_add_i32 m0, s71, 0x800
	s_nop 0
	global_load_lds_dwordx4 v227, s[50:51]
	s_add_i32 m0, s71, 0xc00
	s_nop 0
	global_load_lds_dwordx4 v225, s[50:51]
	s_add_i32 m0, s71, 0x1000
	s_nop 0
	global_load_lds_dwordx4 v230, s[50:51]
	s_add_i32 m0, s71, 0x1400
	s_nop 0
	global_load_lds_dwordx4 v228, s[50:51]
	s_add_i32 m0, s71, 0x1800
	s_nop 0
	global_load_lds_dwordx4 v226, s[50:51]
	s_add_i32 m0, s71, 0x1c00
	s_nop 0
	global_load_lds_dwordx4 v224, s[50:51]
	s_branch .Lat_next
